# diff-attention unit epilogue: sub-layer-norm gain loads hoisted ahead of the store ladder (counted vmcnt instead of vmcnt(0) after each store)
# speedup vs baseline: 1.0019x; 1.0019x over previous
; DI void diff_unit(const Params& p, LAS unsigned char* lds, int layer, float lam, float lam_init, int b, int head, int qb, int tid, int lane, int wave) {
;     ...
;     const float c2 = lam / l; float ss = 0.f;
; #pragma unroll
;     for (int d = 0; d < 4; ++d)
; #pragma unroll
;         for (int g = 0; g < 4; ++g) { const u32x4 w4 = *(const u32x4*)(prow + 16 * d + 8 * (g >> 1)); u32x2 w; w.x = (g & 1) ? w4.z : w4.x; w.y = (g & 1) ? w4.w : w4.y;
;             const float a0 = __builtin_bit_cast(float, w.x << 16), a1 = __builtin_bit_cast(float, w.x & 0xffff0000u), a2 = __builtin_bit_cast(float, w.y << 16), a3 = __builtin_bit_cast(float, w.y & 0xffff0000u);
;             o[d][4 * g] = a0 - c2 * o[d][4 * g]; o[d][4 * g + 1] = a1 - c2 * o[d][4 * g + 1]; o[d][4 * g + 2] = a2 - c2 * o[d][4 * g + 2]; o[d][4 * g + 3] = a3 - c2 * o[d][4 * g + 3];
;             ss += (o[d][4 * g] * o[d][4 * g] + o[d][4 * g + 1] * o[d][4 * g + 1]) + (o[d][4 * g + 2] * o[d][4 * g + 2] + o[d][4 * g + 3] * o[d][4 * g + 3]); }
.LBB0_1780:
	global_load_dwordx4 v[72:75], v[200:201], off offset:32
	global_load_dwordx4 v[76:79], v[200:201], off offset:48
	global_load_dwordx4 v[86:89], v[200:201], off offset:64
	global_load_dwordx4 v[90:93], v[200:201], off offset:80
	global_load_dwordx4 v[64:67], v[200:201], off offset:16
	global_load_dwordx4 v[68:71], v[200:201], off
	global_load_dwordx4 v[94:97], v[200:201], off offset:112
	global_load_dwordx4 v[98:101], v[200:201], off offset:96
	v_pk_add_f32 v[80:81], v[170:171], v[168:169]
	v_mov_b32_e32 v82, v49
	v_mov_b32_e32 v49, v51
	v_mov_b32_e32 v51, v54
	v_mov_b32_e32 v54, v57
	v_mov_b32_e32 v57, v59
	v_mov_b32_e32 v59, v62
	v_add_f32_e32 v62, v80, v81
	v_mov_b32_e32 v83, v50
	v_mov_b32_e32 v50, v53
	v_mov_b32_e32 v53, v55
	v_mov_b32_e32 v55, v58
	v_mov_b32_e32 v58, v61
	v_mov_b32_e32 v61, v63
	ds_bpermute_b32 v63, v205, v62
	v_mov_b32_e32 v103, v34
	v_mov_b32_e32 v102, v33
	v_mov_b32_e32 v33, v35
	v_ashrrev_i32_e32 v197, 31, v196
	s_waitcnt lgkmcnt(0)
	v_add_f32_e32 v34, v62, v63
	v_div_scale_f32 v62, s[0:1], v34, v34, v206
	v_rcp_f32_e32 v63, v62
	v_div_scale_f32 v35, vcc, v206, v34, v206
	s_add_i32 s12, s12, s94
	v_fma_f32 v80, -v62, v63, 1.0
	v_fmac_f32_e32 v63, v80, v63
	v_mul_f32_e32 v80, v35, v63
	v_fma_f32 v81, -v62, v80, v35
	v_fmac_f32_e32 v80, v81, v63
	v_fma_f32 v35, -v62, v80, v35
	v_div_fmas_f32 v35, v35, v63, v80
	v_div_fixup_f32 v84, v35, v34, v206
	s_cmpk_gt_i32 s12, 0x1ff
	s_waitcnt vmcnt(0)
	v_and_b32_e32 v34, 0xffff0000, v72
	v_lshlrev_b32_e32 v35, 16, v73
	v_lshlrev_b32_e32 v62, 16, v72
	v_and_b32_e32 v63, 0xffff0000, v73
	v_and_b32_e32 v72, 0xffff0000, v74
	v_lshlrev_b32_e32 v73, 16, v75
	v_lshlrev_b32_e32 v74, 16, v74
	v_and_b32_e32 v75, 0xffff0000, v75
	v_and_b32_e32 v104, 0xffff0000, v76
	v_lshlrev_b32_e32 v105, 16, v77
	v_and_b32_e32 v112, 0xffff0000, v86
	v_lshlrev_b32_e32 v113, 16, v87
	v_lshlrev_b32_e32 v86, 16, v86
	v_and_b32_e32 v87, 0xffff0000, v87
	v_pk_fma_f32 v[82:83], v[82:83], v[84:85], v[34:35] op_sel_hi:[1,0,1] neg_lo:[1,0,0] neg_hi:[1,0,0]
	v_lshlrev_b32_e32 v106, 16, v76
	v_and_b32_e32 v107, 0xffff0000, v77
	v_and_b32_e32 v108, 0xffff0000, v78
	v_lshlrev_b32_e32 v109, 16, v79
	v_lshlrev_b32_e32 v110, 16, v78
	v_and_b32_e32 v111, 0xffff0000, v79
	v_pk_fma_f32 v[80:81], v[48:49], v[84:85], v[62:63] op_sel_hi:[1,0,1] neg_lo:[1,0,0] neg_hi:[1,0,0]
	v_pk_fma_f32 v[78:79], v[50:51], v[84:85], v[72:73] op_sel_hi:[1,0,1] neg_lo:[1,0,0] neg_hi:[1,0,0]
	v_pk_fma_f32 v[76:77], v[52:53], v[84:85], v[74:75] op_sel_hi:[1,0,1] neg_lo:[1,0,0] neg_hi:[1,0,0]
	v_pk_fma_f32 v[74:75], v[54:55], v[84:85], v[104:105] op_sel_hi:[1,0,1] neg_lo:[1,0,0] neg_hi:[1,0,0]
	v_pk_fma_f32 v[50:51], v[102:103], v[84:85], v[112:113] op_sel_hi:[1,0,1] neg_lo:[1,0,0] neg_hi:[1,0,0]
	v_pk_fma_f32 v[48:49], v[32:33], v[84:85], v[86:87] op_sel_hi:[1,0,1] neg_lo:[1,0,0] neg_hi:[1,0,0]
	v_pk_mul_f32 v[32:33], v[82:83], v[82:83]
	v_pk_fma_f32 v[62:63], v[56:57], v[84:85], v[106:107] op_sel_hi:[1,0,1] neg_lo:[1,0,0] neg_hi:[1,0,0]
	v_pk_mul_f32 v[52:53], v[74:75], v[74:75]
	v_pk_mul_f32 v[56:57], v[50:51], v[50:51]
	v_pk_fma_f32 v[32:33], v[80:81], v[80:81], v[32:33]
	v_pk_fma_f32 v[72:73], v[58:59], v[84:85], v[108:109] op_sel_hi:[1,0,1] neg_lo:[1,0,0] neg_hi:[1,0,0]
	v_pk_fma_f32 v[58:59], v[60:61], v[84:85], v[110:111] op_sel_hi:[1,0,1] neg_lo:[1,0,0] neg_hi:[1,0,0]
	v_pk_mul_f32 v[34:35], v[78:79], v[78:79]
	v_pk_fma_f32 v[52:53], v[62:63], v[62:63], v[52:53]
	v_pk_add_f32 v[60:61], v[32:33], v[32:33] op_sel:[0,1] op_sel_hi:[1,0]
	v_pk_fma_f32 v[32:33], v[48:49], v[48:49], v[56:57]
	v_pk_mul_f32 v[54:55], v[72:73], v[72:73]
	v_pk_fma_f32 v[34:35], v[76:77], v[76:77], v[34:35]
	v_pk_add_f32 v[104:105], v[52:53], v[52:53] op_sel:[0,1] op_sel_hi:[1,0]
	v_pk_add_f32 v[108:109], v[32:33], v[32:33] op_sel:[0,1] op_sel_hi:[1,0]
	v_and_b32_e32 v32, 0xffff0000, v88
	v_lshlrev_b32_e32 v33, 16, v89
	v_mov_b32_e32 v52, v37
	v_mov_b32_e32 v53, v38
	v_pk_fma_f32 v[54:55], v[58:59], v[58:59], v[54:55]
	v_pk_add_f32 v[102:103], v[34:35], v[34:35] op_sel:[0,1] op_sel_hi:[1,0]
	v_lshlrev_b32_e32 v34, 16, v88
	v_and_b32_e32 v35, 0xffff0000, v89
	v_pk_fma_f32 v[56:57], v[52:53], v[84:85], v[32:33] op_sel_hi:[1,0,1] neg_lo:[1,0,0] neg_hi:[1,0,0]
	v_mov_b32_e32 v37, v39
	v_pk_add_f32 v[106:107], v[54:55], v[54:55] op_sel:[0,1] op_sel_hi:[1,0]
	v_pk_fma_f32 v[54:55], v[36:37], v[84:85], v[34:35] op_sel_hi:[1,0,1] neg_lo:[1,0,0] neg_hi:[1,0,0]
	v_pk_mul_f32 v[32:33], v[56:57], v[56:57]
	v_mov_b32_e32 v36, v41
	v_pk_fma_f32 v[32:33], v[54:55], v[54:55], v[32:33]
	v_mov_b32_e32 v37, v42
	v_pk_add_f32 v[110:111], v[32:33], v[32:33] op_sel:[0,1] op_sel_hi:[1,0]
	v_and_b32_e32 v32, 0xffff0000, v90
	v_lshlrev_b32_e32 v33, 16, v91
	v_lshlrev_b32_e32 v34, 16, v90
	v_and_b32_e32 v35, 0xffff0000, v91
	v_pk_fma_f32 v[38:39], v[36:37], v[84:85], v[32:33] op_sel_hi:[1,0,1] neg_lo:[1,0,0] neg_hi:[1,0,0]
	v_mov_b32_e32 v41, v43
	v_pk_fma_f32 v[36:37], v[40:41], v[84:85], v[34:35] op_sel_hi:[1,0,1] neg_lo:[1,0,0] neg_hi:[1,0,0]
	v_pk_mul_f32 v[32:33], v[38:39], v[38:39]
	v_mov_b32_e32 v40, v45
	v_pk_fma_f32 v[32:33], v[36:37], v[36:37], v[32:33]
	v_mov_b32_e32 v41, v46
	v_pk_add_f32 v[90:91], v[32:33], v[32:33] op_sel:[0,1] op_sel_hi:[1,0]
	v_and_b32_e32 v32, 0xffff0000, v92
	v_lshlrev_b32_e32 v33, 16, v93
	v_lshlrev_b32_e32 v34, 16, v92
	v_and_b32_e32 v35, 0xffff0000, v93
	v_pk_fma_f32 v[52:53], v[40:41], v[84:85], v[32:33] op_sel_hi:[1,0,1] neg_lo:[1,0,0] neg_hi:[1,0,0]
	v_mov_b32_e32 v45, v47
	v_pk_fma_f32 v[44:45], v[44:45], v[84:85], v[34:35] op_sel_hi:[1,0,1] neg_lo:[1,0,0] neg_hi:[1,0,0]
	v_pk_mul_f32 v[32:33], v[52:53], v[52:53]
	v_mov_b32_e32 v34, v17
; DI void diff_unit(const Params& p, LAS unsigned char* lds, int layer, float lam, float lam_init, int b, int head, int qb, int tid, int lane, int wave) {
;     ...
;         for (int g = 0; g < 4; ++g) { const u32x4 w4 = *(const u32x4*)(prow + 16 * d + 8 * (g >> 1)); u32x2 w; w.x = (g & 1) ? w4.z : w4.x; w.y = (g & 1) ? w4.w : w4.y;
;             const float a0 = __builtin_bit_cast(float, w.x << 16), a1 = __builtin_bit_cast(float, w.x & 0xffff0000u), a2 = __builtin_bit_cast(float, w.y << 16), a3 = __builtin_bit_cast(float, w.y & 0xffff0000u);
;             o[d][4 * g] = a0 - c2 * o[d][4 * g]; o[d][4 * g + 1] = a1 - c2 * o[d][4 * g + 1]; o[d][4 * g + 2] = a2 - c2 * o[d][4 * g + 2]; o[d][4 * g + 3] = a3 - c2 * o[d][4 * g + 3];
;             ss += (o[d][4 * g] * o[d][4 * g] + o[d][4 * g + 1] * o[d][4 * g + 1]) + (o[d][4 * g + 2] * o[d][4 * g + 2] + o[d][4 * g + 3] * o[d][4 * g + 3]); }
;     ss += __shfl_xor(ss, 32);
;     const float rn = rsqrtf(ss * (1.f / 128.f) + EPS) * (1.f - lam_init);
;     const float* sg = p.in[16] + layer * 128 + 4 * h;
; #pragma unroll
;     for (int d = 0; d < 4; ++d)
; #pragma unroll
;         for (int g = 0; g < 4; g += 2) { const f32x4 gn = *(const f32x4*)(sg + 32 * d + 8 * g), gm = *(const f32x4*)(sg + 32 * d + 8 * g + 8);
	v_pk_fma_f32 v[32:33], v[44:45], v[44:45], v[32:33]
	v_mov_b32_e32 v35, v18
	v_pk_add_f32 v[46:47], v[32:33], v[32:33] op_sel:[0,1] op_sel_hi:[1,0]
	v_and_b32_e32 v32, 0xffff0000, v98
	v_lshlrev_b32_e32 v33, 16, v99
	v_lshlrev_b32_e32 v40, 16, v98
	v_and_b32_e32 v41, 0xffff0000, v99
	v_pk_fma_f32 v[34:35], v[34:35], v[84:85], v[32:33] op_sel_hi:[1,0,1] neg_lo:[1,0,0] neg_hi:[1,0,0]
	v_mov_b32_e32 v17, v19
	v_pk_fma_f32 v[32:33], v[16:17], v[84:85], v[40:41] op_sel_hi:[1,0,1] neg_lo:[1,0,0] neg_hi:[1,0,0]
	v_pk_mul_f32 v[16:17], v[34:35], v[34:35]
	v_mov_b32_e32 v40, v21
	v_pk_fma_f32 v[16:17], v[32:33], v[32:33], v[16:17]
	v_mov_b32_e32 v41, v22
	v_pk_add_f32 v[92:93], v[16:17], v[16:17] op_sel:[0,1] op_sel_hi:[1,0]
	v_and_b32_e32 v16, 0xffff0000, v100
	v_lshlrev_b32_e32 v17, 16, v101
	v_lshlrev_b32_e32 v18, 16, v100
	v_and_b32_e32 v19, 0xffff0000, v101
	v_pk_fma_f32 v[42:43], v[40:41], v[84:85], v[16:17] op_sel_hi:[1,0,1] neg_lo:[1,0,0] neg_hi:[1,0,0]
	v_mov_b32_e32 v21, v23
	v_pk_fma_f32 v[40:41], v[20:21], v[84:85], v[18:19] op_sel_hi:[1,0,1] neg_lo:[1,0,0] neg_hi:[1,0,0]
	v_pk_mul_f32 v[16:17], v[42:43], v[42:43]
	v_mov_b32_e32 v18, v25
	v_pk_fma_f32 v[16:17], v[40:41], v[40:41], v[16:17]
	v_mov_b32_e32 v19, v26
	v_pk_add_f32 v[98:99], v[16:17], v[16:17] op_sel:[0,1] op_sel_hi:[1,0]
	v_and_b32_e32 v16, 0xffff0000, v94
	v_lshlrev_b32_e32 v17, 16, v95
	v_lshlrev_b32_e32 v20, 16, v94
	v_and_b32_e32 v21, 0xffff0000, v95
	v_pk_fma_f32 v[18:19], v[18:19], v[84:85], v[16:17] op_sel_hi:[1,0,1] neg_lo:[1,0,0] neg_hi:[1,0,0]
	v_mov_b32_e32 v25, v27
	v_pk_fma_f32 v[16:17], v[24:25], v[84:85], v[20:21] op_sel_hi:[1,0,1] neg_lo:[1,0,0] neg_hi:[1,0,0]
	v_pk_mul_f32 v[20:21], v[18:19], v[18:19]
	v_mov_b32_e32 v22, v29
	v_pk_fma_f32 v[20:21], v[16:17], v[16:17], v[20:21]
	v_mov_b32_e32 v23, v30
	v_pk_add_f32 v[94:95], v[20:21], v[20:21] op_sel_hi:[0,1]
	v_and_b32_e32 v20, 0xffff0000, v96
	v_lshlrev_b32_e32 v21, 16, v97
	v_lshlrev_b32_e32 v24, 16, v96
	v_and_b32_e32 v25, 0xffff0000, v97
	v_pk_fma_f32 v[22:23], v[22:23], v[84:85], v[20:21] op_sel_hi:[1,0,1] neg_lo:[1,0,0] neg_hi:[1,0,0]
	v_mov_b32_e32 v29, v31
	v_pk_fma_f32 v[20:21], v[28:29], v[84:85], v[24:25] op_sel_hi:[1,0,1] neg_lo:[1,0,0] neg_hi:[1,0,0]
	v_pk_mul_f32 v[24:25], v[22:23], v[22:23]
	v_lshlrev_b32_e32 v96, 16, v71
	v_pk_fma_f32 v[30:31], v[20:21], v[20:21], v[24:25]
	v_lshl_add_u64 v[24:25], v[196:197], 2, s[14:15]
	global_load_dwordx4 v[26:29], v[24:25], off
	global_load_dwordx4 v[86:89], v[24:25], off offset:32
	global_load_dwordx4 v[138:141], v[24:25], off offset:64
	global_load_dwordx4 v[142:145], v[24:25], off offset:96
	global_load_dwordx4 v[146:149], v[24:25], off offset:128
	global_load_dwordx4 v[156:159], v[24:25], off offset:160
	global_load_dwordx4 v[160:163], v[24:25], off offset:192
	global_load_dwordx4 v[164:167], v[24:25], off offset:224
	global_load_dwordx4 v[172:175], v[24:25], off offset:256
	global_load_dwordx4 v[178:181], v[24:25], off offset:288
	global_load_dwordx4 v[210:213], v[24:25], off offset:320
	global_load_dwordx4 v[214:217], v[24:25], off offset:352
	global_load_dwordx4 v[218:221], v[24:25], off offset:384
	global_load_dwordx4 v[222:225], v[24:25], off offset:416
	v_and_b32_e32 v97, 0xffff0000, v71
	v_lshlrev_b32_e32 v100, 16, v70
	v_and_b32_e32 v101, 0xffff0000, v70
	v_pk_fma_f32 v[6:7], v[6:7], v[84:85], v[96:97] op_sel_hi:[1,0,1] neg_lo:[1,0,0] neg_hi:[1,0,0]
	v_pk_fma_f32 v[4:5], v[4:5], v[84:85], v[100:101] op_sel_hi:[1,0,1] neg_lo:[1,0,0] neg_hi:[1,0,0]
	v_mul_f32_e32 v94, v7, v7
	v_mul_f32_e32 v70, v5, v5
	v_pk_fma_f32 v[96:97], v[6:7], v[6:7], v[94:95] op_sel_hi:[1,1,0]
	v_pk_fma_f32 v[70:71], v[4:5], v[4:5], v[70:71] op_sel_hi:[1,1,0]
	v_lshlrev_b32_e32 v100, 16, v68
	v_pk_add_f32 v[70:71], v[70:71], v[96:97]
	v_lshlrev_b32_e32 v96, 16, v69
	v_and_b32_e32 v97, 0xffff0000, v69
	v_and_b32_e32 v101, 0xffff0000, v68
	v_pk_fma_f32 v[96:97], v[2:3], v[84:85], v[96:97] op_sel_hi:[1,0,1] neg_lo:[1,0,0] neg_hi:[1,0,0]
	v_pk_fma_f32 v[0:1], v[0:1], v[84:85], v[100:101] op_sel_hi:[1,0,1] neg_lo:[1,0,0] neg_hi:[1,0,0]
	v_mul_f32_e32 v2, v97, v97
	v_mul_f32_e32 v68, v1, v1
	v_pk_fma_f32 v[2:3], v[96:97], v[96:97], v[2:3] op_sel_hi:[1,1,0]
	v_pk_fma_f32 v[68:69], v[0:1], v[0:1], v[68:69] op_sel_hi:[1,1,0]
	v_mov_b32_e32 v94, v30
	v_pk_add_f32 v[2:3], v[68:69], v[2:3]
	v_lshlrev_b32_e32 v68, 16, v67
	v_pk_add_f32 v[2:3], v[2:3], v[70:71]
	v_and_b32_e32 v69, 0xffff0000, v67
	v_lshlrev_b32_e32 v70, 16, v66
	v_and_b32_e32 v71, 0xffff0000, v66
	v_pk_fma_f32 v[14:15], v[14:15], v[84:85], v[68:69] op_sel_hi:[1,0,1] neg_lo:[1,0,0] neg_hi:[1,0,0]
	v_pk_fma_f32 v[12:13], v[12:13], v[84:85], v[70:71] op_sel_hi:[1,0,1] neg_lo:[1,0,0] neg_hi:[1,0,0]
	v_mul_f32_e32 v68, v15, v15
	v_mul_f32_e32 v66, v13, v13
	v_pk_fma_f32 v[68:69], v[14:15], v[14:15], v[68:69] op_sel_hi:[1,1,0]
	v_pk_fma_f32 v[66:67], v[12:13], v[12:13], v[66:67] op_sel_hi:[1,1,0]
	v_lshlrev_b32_e32 v70, 16, v64
	v_pk_add_f32 v[66:67], v[66:67], v[68:69]
	v_lshlrev_b32_e32 v68, 16, v65
	v_and_b32_e32 v69, 0xffff0000, v65
	v_and_b32_e32 v71, 0xffff0000, v64
	v_pk_fma_f32 v[68:69], v[10:11], v[84:85], v[68:69] op_sel_hi:[1,0,1] neg_lo:[1,0,0] neg_hi:[1,0,0]
	v_pk_fma_f32 v[64:65], v[8:9], v[84:85], v[70:71] op_sel_hi:[1,0,1] neg_lo:[1,0,0] neg_hi:[1,0,0]
	v_mul_f32_e32 v10, v69, v69
	v_mul_f32_e32 v8, v65, v65
	v_pk_fma_f32 v[10:11], v[68:69], v[68:69], v[10:11] op_sel_hi:[1,1,0]
	v_pk_fma_f32 v[8:9], v[64:65], v[64:65], v[8:9] op_sel_hi:[1,1,0]
	s_nop 0
	v_pk_add_f32 v[8:9], v[8:9], v[10:11]
	s_nop 0
	v_pk_add_f32 v[2:3], v[2:3], v[8:9]
	s_nop 0
	v_pk_add_f32 v[2:3], v[66:67], v[2:3]
	s_nop 0
	v_pk_add_f32 v[2:3], v[60:61], v[2:3]
	s_nop 0
	v_pk_add_f32 v[2:3], v[102:103], v[2:3]
	s_nop 0
	v_pk_add_f32 v[2:3], v[104:105], v[2:3]
	s_nop 0
	v_pk_add_f32 v[2:3], v[106:107], v[2:3]
	s_nop 0
	v_pk_add_f32 v[2:3], v[108:109], v[2:3]
	s_nop 0
	v_pk_add_f32 v[2:3], v[110:111], v[2:3]
	s_nop 0
	v_pk_add_f32 v[2:3], v[90:91], v[2:3]
	s_nop 0
	v_pk_add_f32 v[2:3], v[46:47], v[2:3]
	s_nop 0
	v_pk_add_f32 v[2:3], v[92:93], v[2:3]
	s_nop 0
	v_pk_add_f32 v[2:3], v[98:99], v[2:3]
	s_nop 0
	v_pk_mov_b32 v[2:3], v[30:31], v[2:3] op_sel:[1,0]
	s_nop 0
	v_pk_add_f32 v[2:3], v[94:95], v[2:3]
	s_nop 0
	v_add_f32_e32 v2, v2, v3
	ds_bpermute_b32 v3, v205, v2
	s_waitcnt lgkmcnt(0)
; DI void diff_unit(const Params& p, LAS unsigned char* lds, int layer, float lam, float lam_init, int b, int head, int qb, int tid, int lane, int wave) {
;     ...
;     ss += __shfl_xor(ss, 32);
;     const float rn = rsqrtf(ss * (1.f / 128.f) + EPS) * (1.f - lam_init);
;     const float* sg = p.in[16] + layer * 128 + 4 * h;
; #pragma unroll
;     for (int d = 0; d < 4; ++d)
; #pragma unroll
;         for (int g = 0; g < 4; g += 2) { const f32x4 gn = *(const f32x4*)(sg + 32 * d + 8 * g), gm = *(const f32x4*)(sg + 32 * d + 8 * g + 8);
;             const f32x4 v0 = {o[d][4 * g] * rn * gn[0], o[d][4 * g + 1] * rn * gn[1], o[d][4 * g + 2] * rn * gn[2], o[d][4 * g + 3] * rn * gn[3]};
;             const f32x4 v1 = {o[d][4 * g + 4] * rn * gm[0], o[d][4 * g + 5] * rn * gm[1], o[d][4 * g + 6] * rn * gm[2], o[d][4 * g + 7] * rn * gm[3]};
;             st_x16(orow - 4 * h + 32 * d + 8 * g, h, v0, v1); }
	v_add_f32_e32 v2, v2, v3
	v_fmamk_f32 v2, v2, 0x3c000000, v232
	v_mul_f32_e32 v3, 0x4b800000, v2
	v_cmp_gt_f32_e32 vcc, s74, v2
	s_nop 1
	v_cndmask_b32_e32 v2, v2, v3, vcc
	v_rsq_f32_e32 v2, v2
	s_nop 0
	v_mul_f32_e32 v3, 0x45800000, v2
	v_cndmask_b32_e32 v2, v2, v3, vcc
	v_mul_f32_e32 v2, v207, v2
	v_pk_mul_f32 v[0:1], v[0:1], v[2:3] op_sel_hi:[1,0]
	v_pk_mul_f32 v[8:9], v[96:97], v[2:3] op_sel_hi:[1,0]
	v_pk_mul_f32 v[4:5], v[4:5], v[2:3] op_sel_hi:[1,0]
	v_pk_mul_f32 v[6:7], v[6:7], v[2:3] op_sel_hi:[1,0]
	s_waitcnt vmcnt(13)
	v_pk_mul_f32 v[0:1], v[26:27], v[0:1]
	v_pk_mul_f32 v[8:9], v[28:29], v[8:9]
	s_waitcnt vmcnt(12)
	v_pk_mul_f32 v[4:5], v[86:87], v[4:5]
	v_pk_mul_f32 v[6:7], v[88:89], v[6:7]
	v_cvt_pk_bf16_f32 v3, v0, v1
	v_cvt_pk_bf16_f32 v8, v8, v9
	v_cvt_pk_bf16_f32 v9, v4, v5
	v_cvt_pk_bf16_f32 v7, v6, v7
	v_cmp_gt_u32_e32 vcc, 32, v208
	v_pk_mul_f32 v[26:27], v[64:65], v[2:3] op_sel_hi:[1,0]
	v_pk_mul_f32 v[12:13], v[12:13], v[2:3] op_sel_hi:[1,0]
	v_cndmask_b32_e32 v0, v3, v9, vcc
	v_cndmask_b32_e32 v1, v8, v7, vcc
	ds_bpermute_b32 v6, v205, v0
	ds_bpermute_b32 v10, v205, v1
	v_lshl_add_u64 v[0:1], v[194:195], 1, v[198:199]
	s_waitcnt lgkmcnt(1)
	v_cndmask_b32_e32 v4, v6, v3, vcc
	s_waitcnt lgkmcnt(0)
	v_cndmask_b32_e32 v5, v10, v8, vcc
	v_cndmask_b32_e32 v6, v9, v6, vcc
	v_cndmask_b32_e32 v7, v7, v10, vcc
	global_store_dwordx4 v[0:1], v[4:7], off
	s_waitcnt vmcnt(11)
	v_mov_b64_e32 v[8:9], v[142:143]
	v_mov_b64_e32 v[10:11], v[144:145]
	v_mov_b64_e32 v[4:5], v[138:139]
	v_mov_b64_e32 v[6:7], v[140:141]
	v_pk_mul_f32 v[4:5], v[4:5], v[26:27]
	v_pk_mul_f32 v[26:27], v[68:69], v[2:3] op_sel_hi:[1,0]
	v_pk_mul_f32 v[8:9], v[8:9], v[12:13]
	v_pk_mul_f32 v[12:13], v[14:15], v[2:3] op_sel_hi:[1,0]
	v_pk_mul_f32 v[6:7], v[6:7], v[26:27]
	v_pk_mul_f32 v[10:11], v[10:11], v[12:13]
	v_cvt_pk_bf16_f32 v3, v4, v5
	v_cvt_pk_bf16_f32 v5, v6, v7
	v_cvt_pk_bf16_f32 v6, v8, v9
	v_cvt_pk_bf16_f32 v7, v10, v11
	v_cndmask_b32_e32 v4, v3, v6, vcc
	v_cndmask_b32_e32 v8, v5, v7, vcc
	ds_bpermute_b32 v9, v205, v4
	ds_bpermute_b32 v8, v205, v8
	v_mov_b32_e32 v12, v80
	v_mov_b32_e32 v13, v82
	v_pk_mul_f32 v[12:13], v[12:13], v[2:3] op_sel_hi:[1,0]
	s_waitcnt lgkmcnt(1)
	v_cndmask_b32_e32 v4, v9, v3, vcc
	s_waitcnt lgkmcnt(0)
	v_cndmask_b32_e32 v5, v8, v5, vcc
	v_cndmask_b32_e32 v6, v6, v9, vcc
	v_cndmask_b32_e32 v7, v7, v8, vcc
	global_store_dwordx4 v[0:1], v[4:7], off offset:32
	s_waitcnt vmcnt(10)
	v_mov_b64_e32 v[8:9], v[156:157]
	v_mov_b64_e32 v[10:11], v[158:159]
	v_mov_b64_e32 v[4:5], v[146:147]
	v_mov_b64_e32 v[6:7], v[148:149]
	v_mov_b32_e32 v80, v83
	v_pk_mul_f32 v[14:15], v[80:81], v[2:3] op_sel_hi:[1,0]
	v_pk_mul_f32 v[4:5], v[4:5], v[12:13]
	v_mov_b32_e32 v12, v76
	v_mov_b32_e32 v13, v78
	v_pk_mul_f32 v[12:13], v[12:13], v[2:3] op_sel_hi:[1,0]
	v_mov_b32_e32 v76, v79
	v_pk_mul_f32 v[8:9], v[8:9], v[12:13]
	v_pk_mul_f32 v[12:13], v[76:77], v[2:3] op_sel_hi:[1,0]
	v_pk_mul_f32 v[6:7], v[6:7], v[14:15]
	v_pk_mul_f32 v[10:11], v[10:11], v[12:13]
	v_cvt_pk_bf16_f32 v3, v4, v5
	v_cvt_pk_bf16_f32 v5, v6, v7
	v_cvt_pk_bf16_f32 v6, v8, v9
	v_cvt_pk_bf16_f32 v7, v10, v11
	v_cndmask_b32_e32 v4, v3, v6, vcc
	v_cndmask_b32_e32 v8, v5, v7, vcc
	ds_bpermute_b32 v9, v205, v4
	ds_bpermute_b32 v8, v205, v8
	v_mov_b32_e32 v12, v62
	v_mov_b32_e32 v13, v74
	v_mov_b32_e32 v14, v58
	s_waitcnt lgkmcnt(1)
	v_cndmask_b32_e32 v4, v9, v3, vcc
	s_waitcnt lgkmcnt(0)
	v_cndmask_b32_e32 v5, v8, v5, vcc
	v_cndmask_b32_e32 v6, v6, v9, vcc
	v_cndmask_b32_e32 v7, v7, v8, vcc
	global_store_dwordx4 v[0:1], v[4:7], off offset:64
	s_waitcnt vmcnt(9)
	v_mov_b64_e32 v[8:9], v[164:165]
	v_mov_b64_e32 v[10:11], v[166:167]
	v_mov_b64_e32 v[4:5], v[160:161]
	v_mov_b64_e32 v[6:7], v[162:163]
	v_mov_b32_e32 v15, v72
	v_mov_b32_e32 v62, v75
	v_mov_b32_e32 v58, v73
	v_pk_mul_f32 v[12:13], v[12:13], v[2:3] op_sel_hi:[1,0]
	v_pk_mul_f32 v[26:27], v[62:63], v[2:3] op_sel_hi:[1,0]
	v_pk_mul_f32 v[14:15], v[14:15], v[2:3] op_sel_hi:[1,0]
	v_pk_mul_f32 v[28:29], v[58:59], v[2:3] op_sel_hi:[1,0]
	v_pk_mul_f32 v[4:5], v[4:5], v[12:13]
	v_pk_mul_f32 v[6:7], v[6:7], v[26:27]
	v_pk_mul_f32 v[8:9], v[8:9], v[14:15]
	v_pk_mul_f32 v[10:11], v[10:11], v[28:29]
	v_cvt_pk_bf16_f32 v3, v4, v5
	v_cvt_pk_bf16_f32 v5, v6, v7
	v_cvt_pk_bf16_f32 v6, v8, v9
	v_cvt_pk_bf16_f32 v7, v10, v11
	v_cndmask_b32_e32 v4, v3, v6, vcc
	v_cndmask_b32_e32 v8, v5, v7, vcc
	ds_bpermute_b32 v9, v205, v4
	ds_bpermute_b32 v8, v205, v8
	v_mov_b32_e32 v12, v48
	v_mov_b32_e32 v13, v50
	v_mov_b32_e32 v14, v54
	s_waitcnt lgkmcnt(1)
	v_cndmask_b32_e32 v4, v9, v3, vcc
	s_waitcnt lgkmcnt(0)
	v_cndmask_b32_e32 v5, v8, v5, vcc
	v_cndmask_b32_e32 v6, v6, v9, vcc
	v_cndmask_b32_e32 v7, v7, v8, vcc
	global_store_dwordx4 v[0:1], v[4:7], off offset:96
	s_waitcnt vmcnt(8)
; DI void diff_unit(const Params& p, LAS unsigned char* lds, int layer, float lam, float lam_init, int b, int head, int qb, int tid, int lane, int wave) {
;     ...
; #pragma unroll
;     for (int d = 0; d < 4; ++d)
; #pragma unroll
;         for (int g = 0; g < 4; g += 2) { const f32x4 gn = *(const f32x4*)(sg + 32 * d + 8 * g), gm = *(const f32x4*)(sg + 32 * d + 8 * g + 8);
;             const f32x4 v0 = {o[d][4 * g] * rn * gn[0], o[d][4 * g + 1] * rn * gn[1], o[d][4 * g + 2] * rn * gn[2], o[d][4 * g + 3] * rn * gn[3]};
;             const f32x4 v1 = {o[d][4 * g + 4] * rn * gm[0], o[d][4 * g + 5] * rn * gm[1], o[d][4 * g + 6] * rn * gm[2], o[d][4 * g + 7] * rn * gm[3]};
;             st_x16(orow - 4 * h + 32 * d + 8 * g, h, v0, v1); }
	v_mov_b64_e32 v[8:9], v[178:179]
	v_mov_b64_e32 v[10:11], v[180:181]
	v_mov_b64_e32 v[4:5], v[172:173]
	v_mov_b64_e32 v[6:7], v[174:175]
	v_mov_b32_e32 v15, v56
	v_mov_b32_e32 v48, v51
	v_mov_b32_e32 v54, v57
	v_pk_mul_f32 v[12:13], v[12:13], v[2:3] op_sel_hi:[1,0]
	v_pk_mul_f32 v[26:27], v[48:49], v[2:3] op_sel_hi:[1,0]
	v_pk_mul_f32 v[14:15], v[14:15], v[2:3] op_sel_hi:[1,0]
	v_pk_mul_f32 v[28:29], v[54:55], v[2:3] op_sel_hi:[1,0]
	v_pk_mul_f32 v[4:5], v[4:5], v[12:13]
	v_pk_mul_f32 v[6:7], v[6:7], v[26:27]
	v_pk_mul_f32 v[8:9], v[8:9], v[14:15]
	v_pk_mul_f32 v[10:11], v[10:11], v[28:29]
	v_cvt_pk_bf16_f32 v3, v4, v5
	v_cvt_pk_bf16_f32 v5, v6, v7
	v_cvt_pk_bf16_f32 v6, v8, v9
	v_cvt_pk_bf16_f32 v7, v10, v11
	v_cndmask_b32_e32 v4, v3, v6, vcc
	v_cndmask_b32_e32 v8, v5, v7, vcc
	ds_bpermute_b32 v9, v205, v4
	ds_bpermute_b32 v8, v205, v8
	v_mov_b32_e32 v12, v36
	v_mov_b32_e32 v13, v38
	v_mov_b32_e32 v14, v44
	s_waitcnt lgkmcnt(1)
	v_cndmask_b32_e32 v4, v9, v3, vcc
	s_waitcnt lgkmcnt(0)
	v_cndmask_b32_e32 v5, v8, v5, vcc
	v_cndmask_b32_e32 v6, v6, v9, vcc
	v_cndmask_b32_e32 v7, v7, v8, vcc
	global_store_dwordx4 v[0:1], v[4:7], off offset:128
	s_waitcnt vmcnt(7)
	v_mov_b64_e32 v[8:9], v[214:215]
	v_mov_b64_e32 v[10:11], v[216:217]
	v_mov_b64_e32 v[4:5], v[210:211]
	v_mov_b64_e32 v[6:7], v[212:213]
	v_mov_b32_e32 v15, v52
	v_mov_b32_e32 v36, v39
	v_mov_b32_e32 v44, v53
	v_pk_mul_f32 v[12:13], v[12:13], v[2:3] op_sel_hi:[1,0]
	v_pk_mul_f32 v[26:27], v[36:37], v[2:3] op_sel_hi:[1,0]
	v_pk_mul_f32 v[14:15], v[14:15], v[2:3] op_sel_hi:[1,0]
	v_pk_mul_f32 v[28:29], v[44:45], v[2:3] op_sel_hi:[1,0]
	v_pk_mul_f32 v[4:5], v[12:13], v[4:5]
	v_pk_mul_f32 v[6:7], v[26:27], v[6:7]
	v_pk_mul_f32 v[8:9], v[14:15], v[8:9]
	v_pk_mul_f32 v[10:11], v[28:29], v[10:11]
	v_cvt_pk_bf16_f32 v3, v4, v5
	v_cvt_pk_bf16_f32 v5, v6, v7
	v_cvt_pk_bf16_f32 v6, v8, v9
	v_cvt_pk_bf16_f32 v7, v10, v11
	v_cndmask_b32_e32 v4, v3, v6, vcc
	v_cndmask_b32_e32 v8, v5, v7, vcc
	ds_bpermute_b32 v9, v205, v4
	ds_bpermute_b32 v8, v205, v8
	v_mov_b32_e32 v12, v32
	v_mov_b32_e32 v13, v34
	v_mov_b32_e32 v14, v40
	s_waitcnt lgkmcnt(1)
	v_cndmask_b32_e32 v4, v9, v3, vcc
	s_waitcnt lgkmcnt(0)
	v_cndmask_b32_e32 v5, v8, v5, vcc
	v_cndmask_b32_e32 v6, v6, v9, vcc
	v_cndmask_b32_e32 v7, v7, v8, vcc
	global_store_dwordx4 v[0:1], v[4:7], off offset:160
	s_waitcnt vmcnt(6)
	v_mov_b64_e32 v[8:9], v[222:223]
	v_mov_b64_e32 v[10:11], v[224:225]
	v_mov_b64_e32 v[4:5], v[218:219]
	v_mov_b64_e32 v[6:7], v[220:221]
	v_mov_b32_e32 v15, v42
	v_mov_b32_e32 v32, v35
	v_mov_b32_e32 v40, v43
	v_pk_mul_f32 v[12:13], v[12:13], v[2:3] op_sel_hi:[1,0]
	v_pk_mul_f32 v[26:27], v[32:33], v[2:3] op_sel_hi:[1,0]
	v_pk_mul_f32 v[14:15], v[14:15], v[2:3] op_sel_hi:[1,0]
	v_pk_mul_f32 v[28:29], v[40:41], v[2:3] op_sel_hi:[1,0]
	v_pk_mul_f32 v[4:5], v[12:13], v[4:5]
	v_pk_mul_f32 v[6:7], v[26:27], v[6:7]
	v_pk_mul_f32 v[8:9], v[14:15], v[8:9]
	v_pk_mul_f32 v[10:11], v[28:29], v[10:11]
	v_cvt_pk_bf16_f32 v3, v4, v5
	v_cvt_pk_bf16_f32 v5, v6, v7
	v_cvt_pk_bf16_f32 v6, v8, v9
	v_cvt_pk_bf16_f32 v7, v10, v11
	v_cndmask_b32_e32 v4, v3, v6, vcc
	v_cndmask_b32_e32 v8, v5, v7, vcc
	ds_bpermute_b32 v9, v205, v4
	ds_bpermute_b32 v8, v205, v8
	v_mov_b32_e32 v12, v16
	v_mov_b32_e32 v13, v18
	v_mov_b32_e32 v14, v20
	s_waitcnt lgkmcnt(1)
	v_cndmask_b32_e32 v4, v9, v3, vcc
	s_waitcnt lgkmcnt(0)
	v_cndmask_b32_e32 v5, v8, v5, vcc
	v_cndmask_b32_e32 v6, v6, v9, vcc
	v_cndmask_b32_e32 v7, v7, v8, vcc
	global_store_dwordx4 v[0:1], v[4:7], off offset:192
	global_load_dwordx4 v[4:7], v[24:25], off offset:448
	s_nop 0
	global_load_dwordx4 v[8:11], v[24:25], off offset:480
	v_mov_b32_e32 v15, v22
	v_mov_b32_e32 v16, v19
	v_mov_b32_e32 v20, v23
	v_pk_mul_f32 v[12:13], v[12:13], v[2:3] op_sel_hi:[1,0]
	v_pk_mul_f32 v[16:17], v[16:17], v[2:3] op_sel_hi:[1,0]
	v_pk_mul_f32 v[14:15], v[14:15], v[2:3] op_sel_hi:[1,0]
	v_pk_mul_f32 v[2:3], v[20:21], v[2:3] op_sel_hi:[1,0]
	s_waitcnt vmcnt(1)
	v_pk_mul_f32 v[4:5], v[12:13], v[4:5]
	v_pk_mul_f32 v[6:7], v[16:17], v[6:7]
	s_waitcnt vmcnt(0)
	v_pk_mul_f32 v[8:9], v[14:15], v[8:9]
	v_pk_mul_f32 v[2:3], v[2:3], v[10:11]
	v_cvt_pk_bf16_f32 v4, v4, v5
	v_cvt_pk_bf16_f32 v5, v6, v7
	v_cvt_pk_bf16_f32 v6, v8, v9
	v_cvt_pk_bf16_f32 v7, v2, v3
	v_cndmask_b32_e32 v2, v4, v6, vcc
	v_cndmask_b32_e32 v3, v5, v7, vcc
	ds_bpermute_b32 v8, v205, v2
	ds_bpermute_b32 v9, v205, v3
	s_waitcnt lgkmcnt(1)
	v_cndmask_b32_e32 v2, v8, v4, vcc
	s_waitcnt lgkmcnt(0)
	v_cndmask_b32_e32 v3, v9, v5, vcc
	v_cndmask_b32_e32 v4, v6, v8, vcc
	v_cndmask_b32_e32 v5, v7, v9, vcc
	global_store_dwordx4 v[0:1], v[2:5], off offset:224
	s_cbranch_scc1 .LBB0_1909
